# all per-phase setprio flips deleted; one static s_setprio 1 for waves 4-7 at kernel entry
# baseline (speedup 1.0000x reference)
_Z10fwd_kernel4Args:
	s_load_dwordx2 s[12:13], s[0:1], 0x100
	s_add_u32 s74, s0, 0x100
	v_and_b32_e32 v218, 0x3ff, v0
	s_mov_b32 s97, s2
	s_addc_u32 s75, s1, 0
	s_mov_b64 s[4:5], s[0:1]
	v_readfirstlane_b32 s100, v0
	s_nop 3
	s_and_b32 s100, s100, 0x3ff
	s_lshr_b32 s100, s100, 6
	s_cmp_ge_u32 s100, 4
	s_cbranch_scc0 .Lprio_done
	s_setprio 1
.Lprio_done:
	v_cmp_eq_u32_e32 vcc, 0, v218
	s_and_saveexec_b64 s[2:3], vcc
	s_cbranch_execz .LBB0_3
	s_add_i32 s8, 0, 0x23fc0
	v_mov_b32_e32 v1, 0
	v_mov_b32_e32 v2, s8
	s_add_i32 s8, 0, 0x23fc4
	s_mov_b64 s[6:7], exec
	ds_write_b32 v2, v1
	v_mov_b32_e32 v2, s8
	ds_write_b32 v2, v1
	v_mbcnt_lo_u32_b32 v1, s6, 0
	v_mbcnt_hi_u32_b32 v1, s7, v1
	v_cmp_eq_u32_e32 vcc, 0, v1
	s_getreg_b32 s8, hwreg(HW_REG_XCC_ID, 0, 4)
	s_and_b64 s[10:11], exec, vcc
	s_mov_b64 exec, s[10:11]
	s_cbranch_execz .LBB0_3
	s_load_dwordx2 s[4:5], s[4:5], 0xf0
	s_lshl_b32 s8, s8, 8
	s_and_b32 s8, s8, 0xf00
	v_mov_b32_e32 v1, 0x10000
	s_waitcnt lgkmcnt(0)
	s_add_u32 s4, s4, s8
	s_addc_u32 s5, s5, 0
	s_bcnt1_i32_b64 s6, s[6:7]
	v_mov_b32_e32 v2, s6
	global_atomic_add v1, v2, s[4:5] offset:1024
	s_lshr_b32 s6, s8, 8
	s_and_b32 s7, s97, 7
	s_sub_u32 s4, s4, s8
	s_subb_u32 s5, s5, 0
	s_add_u32 s4, s4, 0x14000
	s_addc_u32 s5, s5, 0
	s_lshl_b32 s7, s7, 2
	s_add_i32 s8, s6, 1
	s_sub_i32 s6, 16, s6
	v_mov_b32_e32 v1, s7
	v_mov_b32_e32 v2, s8
	v_mov_b32_e32 v3, s6
	s_nop 1
	global_atomic_umax v1, v2, s[4:5] offset:64
	global_atomic_umax v1, v3, s[4:5] offset:128
